# attention online softmax: lazy rescaling (keep the running row max while the new tile exceeds it by <= 8 in the log2 domain; accumulator rescale skipped for the whole wave)
# speedup vs baseline: 1.0091x; 1.0066x over previous
.Lat_noload_A:
	v_add_u32_e32 v193, s44, v164
	v_add_u32_e32 v194, s1, v168
	s_setprio 0
	ds_read_b128 v[204:207], v193
	ds_read_b128 v[208:211], v193 offset:6656
	ds_read_b128 v[212:215], v193 offset:13312
	ds_read_b128 v[216:219], v193 offset:19968
	ds_read_b128 v[220:223], v193 offset:64
	ds_read_b128 v[224:227], v193 offset:6720
	ds_read_b128 v[228:231], v193 offset:13376
	ds_read_b128 v[232:235], v193 offset:20032
	s_waitcnt lgkmcnt(7)
	v_mfma_f32_16x16x32_bf16 v[132:135], v[204:207], v[64:67], 0
	v_mfma_f32_16x16x32_bf16 v[136:139], v[204:207], v[88:91], 0
	ds_read_b128 v[204:207], v193 offset:128
	s_waitcnt lgkmcnt(7)
	v_mfma_f32_16x16x32_bf16 v[140:143], v[208:211], v[64:67], 0
	v_mfma_f32_16x16x32_bf16 v[144:147], v[208:211], v[88:91], 0
	ds_read_b128 v[208:211], v193 offset:6784
	s_waitcnt lgkmcnt(7)
	v_mfma_f32_16x16x32_bf16 v[148:151], v[212:215], v[64:67], 0
	v_mfma_f32_16x16x32_bf16 v[152:155], v[212:215], v[88:91], 0
	ds_read_b128 v[212:215], v193 offset:13440
	s_waitcnt lgkmcnt(7)
	v_mfma_f32_16x16x32_bf16 v[156:159], v[216:219], v[64:67], 0
	v_mfma_f32_16x16x32_bf16 v[160:163], v[216:219], v[88:91], 0
	ds_read_b128 v[216:219], v193 offset:20096
	s_waitcnt lgkmcnt(7)
	v_mfma_f32_16x16x32_bf16 v[132:135], v[220:223], v[68:71], v[132:135]
	v_mfma_f32_16x16x32_bf16 v[136:139], v[220:223], v[92:95], v[136:139]
	ds_read_b128 v[220:223], v193 offset:192
	s_waitcnt lgkmcnt(7)
	v_mfma_f32_16x16x32_bf16 v[140:143], v[224:227], v[68:71], v[140:143]
	v_mfma_f32_16x16x32_bf16 v[144:147], v[224:227], v[92:95], v[144:147]
	ds_read_b128 v[224:227], v193 offset:6848
	s_waitcnt lgkmcnt(7)
	v_mfma_f32_16x16x32_bf16 v[148:151], v[228:231], v[68:71], v[148:151]
	v_mfma_f32_16x16x32_bf16 v[152:155], v[228:231], v[92:95], v[152:155]
	ds_read_b128 v[228:231], v193 offset:13504
	s_waitcnt lgkmcnt(7)
	v_mfma_f32_16x16x32_bf16 v[156:159], v[232:235], v[68:71], v[156:159]
	v_mfma_f32_16x16x32_bf16 v[160:163], v[232:235], v[92:95], v[160:163]
	ds_read_b128 v[232:235], v193 offset:20160
	s_waitcnt lgkmcnt(7)
	v_mfma_f32_16x16x32_bf16 v[132:135], v[204:207], v[72:75], v[132:135]
	v_mfma_f32_16x16x32_bf16 v[136:139], v[204:207], v[96:99], v[136:139]
	ds_read_b128 v[204:207], v193 offset:256
	s_waitcnt lgkmcnt(7)
	v_mfma_f32_16x16x32_bf16 v[140:143], v[208:211], v[72:75], v[140:143]
	v_mfma_f32_16x16x32_bf16 v[144:147], v[208:211], v[96:99], v[144:147]
	ds_read_b128 v[208:211], v193 offset:6912
	s_waitcnt lgkmcnt(7)
	v_mfma_f32_16x16x32_bf16 v[148:151], v[212:215], v[72:75], v[148:151]
	v_mfma_f32_16x16x32_bf16 v[152:155], v[212:215], v[96:99], v[152:155]
	ds_read_b128 v[212:215], v193 offset:13568
	s_waitcnt lgkmcnt(7)
	v_mfma_f32_16x16x32_bf16 v[156:159], v[216:219], v[72:75], v[156:159]
	v_mfma_f32_16x16x32_bf16 v[160:163], v[216:219], v[96:99], v[160:163]
	ds_read_b128 v[216:219], v193 offset:20224
	s_waitcnt lgkmcnt(7)
	v_mfma_f32_16x16x32_bf16 v[132:135], v[220:223], v[76:79], v[132:135]
	v_mfma_f32_16x16x32_bf16 v[136:139], v[220:223], v[100:103], v[136:139]
	ds_read_b128 v[220:223], v193 offset:320
	s_waitcnt lgkmcnt(7)
	v_mfma_f32_16x16x32_bf16 v[140:143], v[224:227], v[76:79], v[140:143]
	v_mfma_f32_16x16x32_bf16 v[144:147], v[224:227], v[100:103], v[144:147]
	ds_read_b128 v[224:227], v193 offset:6976
	s_waitcnt lgkmcnt(7)
	v_mfma_f32_16x16x32_bf16 v[148:151], v[228:231], v[76:79], v[148:151]
	v_mfma_f32_16x16x32_bf16 v[152:155], v[228:231], v[100:103], v[152:155]
	ds_read_b128 v[228:231], v193 offset:13632
	s_waitcnt lgkmcnt(7)
	v_mfma_f32_16x16x32_bf16 v[156:159], v[232:235], v[76:79], v[156:159]
	v_mfma_f32_16x16x32_bf16 v[160:163], v[232:235], v[100:103], v[160:163]
	ds_read_b128 v[232:235], v193 offset:20288
	s_waitcnt lgkmcnt(7)
	v_mfma_f32_16x16x32_bf16 v[132:135], v[204:207], v[80:83], v[132:135]
	v_mfma_f32_16x16x32_bf16 v[136:139], v[204:207], v[104:107], v[136:139]
	ds_read_b128 v[204:207], v194
	s_waitcnt lgkmcnt(7)
	v_mfma_f32_16x16x32_bf16 v[140:143], v[208:211], v[80:83], v[140:143]
	v_mfma_f32_16x16x32_bf16 v[144:147], v[208:211], v[104:107], v[144:147]
	ds_read_b128 v[208:211], v194 offset:64
	s_waitcnt lgkmcnt(7)
	v_mfma_f32_16x16x32_bf16 v[148:151], v[212:215], v[80:83], v[148:151]
	v_mfma_f32_16x16x32_bf16 v[152:155], v[212:215], v[104:107], v[152:155]
	ds_read_b128 v[212:215], v194 offset:2560
	s_waitcnt lgkmcnt(7)
	v_mfma_f32_16x16x32_bf16 v[156:159], v[216:219], v[80:83], v[156:159]
	v_mfma_f32_16x16x32_bf16 v[160:163], v[216:219], v[104:107], v[160:163]
	ds_read_b128 v[216:219], v194 offset:2624
	s_waitcnt lgkmcnt(7)
	v_mfma_f32_16x16x32_bf16 v[132:135], v[220:223], v[84:87], v[132:135]
	v_mfma_f32_16x16x32_bf16 v[136:139], v[220:223], v[108:111], v[136:139]
	ds_read_b128 v[220:223], v194 offset:5120
	s_waitcnt lgkmcnt(7)
	v_mfma_f32_16x16x32_bf16 v[140:143], v[224:227], v[84:87], v[140:143]
	v_mfma_f32_16x16x32_bf16 v[144:147], v[224:227], v[108:111], v[144:147]
	ds_read_b128 v[224:227], v194 offset:5184
	s_waitcnt lgkmcnt(7)
	v_mfma_f32_16x16x32_bf16 v[148:151], v[228:231], v[84:87], v[148:151]
	v_mfma_f32_16x16x32_bf16 v[152:155], v[228:231], v[108:111], v[152:155]
	ds_read_b128 v[228:231], v194 offset:7680
	s_waitcnt lgkmcnt(7)
	v_mfma_f32_16x16x32_bf16 v[156:159], v[232:235], v[84:87], v[156:159]
	v_mfma_f32_16x16x32_bf16 v[160:163], v[232:235], v[108:111], v[160:163]
	ds_read_b128 v[232:235], v194 offset:7744
	s_setprio 1
	s_nop 6
	v_max3_f32 v199, v132, v133, v134
	v_max3_f32 v200, v136, v137, v138
	v_max3_f32 v199, v199, v135, v140
	v_max3_f32 v200, v200, v139, v144
	v_max3_f32 v199, v199, v141, v142
	v_max3_f32 v200, v200, v145, v146
	v_max3_f32 v199, v199, v143, v148
	v_max3_f32 v200, v200, v147, v152
	v_max3_f32 v199, v199, v149, v150
	v_max3_f32 v200, v200, v153, v154
	v_max3_f32 v199, v199, v151, v156
	v_max3_f32 v200, v200, v155, v160
	v_max3_f32 v199, v199, v157, v158
	v_max3_f32 v200, v200, v161, v162
	v_max_f32_e32 v199, v199, v159
	v_max_f32_e32 v200, v200, v163
	v_mov_b32_e32 v253, v199
	v_mov_b32_e32 v201, v200
	s_nop 1
	v_permlane16_swap_b32_e32 v199, v253
	v_permlane16_swap_b32_e32 v200, v201
	s_nop 0
	v_max_f32_e32 v199, v199, v253
	v_max_f32_e32 v200, v200, v201
	v_mov_b32_e32 v253, v199
	v_mov_b32_e32 v201, v200
	s_nop 1
	v_permlane32_swap_b32_e32 v199, v253
	v_permlane32_swap_b32_e32 v200, v201
	s_nop 0
	v_max_f32_e32 v199, v199, v253
	v_max_f32_e32 v200, v200, v201
	v_max_f32_e32 v199, v177, v199
	v_max_f32_e32 v200, v178, v200
	v_sub_f32_e32 v182, v177, v199
	v_sub_f32_e32 v202, v178, v200
	v_cmp_le_f32_e32 vcc, 0xc1000000, v182
	s_nop 1
	v_cndmask_b32_e32 v199, v199, v177, vcc
	v_cmp_le_f32_e32 vcc, 0xc1000000, v202
	s_nop 1
	v_cndmask_b32_e32 v200, v200, v178, vcc
	v_sub_f32_e32 v182, v177, v199
	v_sub_f32_e32 v202, v178, v200
	v_exp_f32_e32 v182, v182
	v_exp_f32_e32 v202, v202
	v_mov_b32_e32 v177, v199
	v_mov_b32_e32 v178, v200
	v_sub_f32_e32 v132, v132, v177
	v_sub_f32_e32 v136, v136, v178
	v_sub_f32_e32 v133, v133, v177
	v_sub_f32_e32 v137, v137, v178
	v_sub_f32_e32 v134, v134, v177
	v_sub_f32_e32 v138, v138, v178
	v_sub_f32_e32 v135, v135, v177
	v_sub_f32_e32 v139, v139, v178
	v_sub_f32_e32 v140, v140, v177
	v_sub_f32_e32 v144, v144, v178
	v_sub_f32_e32 v141, v141, v177
	v_sub_f32_e32 v145, v145, v178
	v_sub_f32_e32 v142, v142, v177
	v_sub_f32_e32 v146, v146, v178
	v_sub_f32_e32 v143, v143, v177
	v_sub_f32_e32 v147, v147, v178
	v_sub_f32_e32 v148, v148, v177
	v_sub_f32_e32 v152, v152, v178
	v_sub_f32_e32 v149, v149, v177
	v_sub_f32_e32 v153, v153, v178
	v_sub_f32_e32 v150, v150, v177
	v_sub_f32_e32 v154, v154, v178
	v_sub_f32_e32 v151, v151, v177
	v_sub_f32_e32 v155, v155, v178
	v_sub_f32_e32 v156, v156, v177
	v_sub_f32_e32 v160, v160, v178
	v_sub_f32_e32 v157, v157, v177
	v_sub_f32_e32 v161, v161, v178
	v_sub_f32_e32 v158, v158, v177
	v_sub_f32_e32 v162, v162, v178
	v_sub_f32_e32 v159, v159, v177
	v_sub_f32_e32 v163, v163, v178
	v_exp_f32_e32 v132, v132
	v_exp_f32_e32 v136, v136
	v_exp_f32_e32 v133, v133
	v_exp_f32_e32 v137, v137
	v_exp_f32_e32 v134, v134
	v_exp_f32_e32 v138, v138
	v_exp_f32_e32 v135, v135
	v_exp_f32_e32 v139, v139
	v_exp_f32_e32 v140, v140
	v_exp_f32_e32 v144, v144
	v_exp_f32_e32 v141, v141
	v_exp_f32_e32 v145, v145
	v_exp_f32_e32 v142, v142
	v_exp_f32_e32 v146, v146
	v_exp_f32_e32 v143, v143
	v_exp_f32_e32 v147, v147
	v_exp_f32_e32 v148, v148
	v_exp_f32_e32 v152, v152
	v_exp_f32_e32 v149, v149
	v_exp_f32_e32 v153, v153
	v_exp_f32_e32 v150, v150
	v_exp_f32_e32 v154, v154
	v_exp_f32_e32 v151, v151
	v_exp_f32_e32 v155, v155
	v_exp_f32_e32 v156, v156
	v_exp_f32_e32 v160, v160
	v_exp_f32_e32 v157, v157
	v_exp_f32_e32 v161, v161
	v_exp_f32_e32 v158, v158
	v_exp_f32_e32 v162, v162
	v_exp_f32_e32 v159, v159
	v_exp_f32_e32 v163, v163
	v_cmp_eq_f32_e32 vcc, 1.0, v182
	s_cmp_eq_u64 vcc, exec
	s_cbranch_scc1 .Lat_noscale0_A
	v_pk_mul_f32 v[0:1], v[0:1], v[182:183] op_sel_hi:[1,0]
	v_pk_mul_f32 v[2:3], v[2:3], v[182:183] op_sel_hi:[1,0]
	v_pk_mul_f32 v[8:9], v[8:9], v[182:183] op_sel_hi:[1,0]
	v_pk_mul_f32 v[10:11], v[10:11], v[182:183] op_sel_hi:[1,0]
	v_pk_mul_f32 v[16:17], v[16:17], v[182:183] op_sel_hi:[1,0]
	v_pk_mul_f32 v[18:19], v[18:19], v[182:183] op_sel_hi:[1,0]
	v_pk_mul_f32 v[24:25], v[24:25], v[182:183] op_sel_hi:[1,0]
	v_pk_mul_f32 v[26:27], v[26:27], v[182:183] op_sel_hi:[1,0]
	v_pk_mul_f32 v[32:33], v[32:33], v[182:183] op_sel_hi:[1,0]
	v_pk_mul_f32 v[34:35], v[34:35], v[182:183] op_sel_hi:[1,0]
	v_pk_mul_f32 v[40:41], v[40:41], v[182:183] op_sel_hi:[1,0]
	v_pk_mul_f32 v[42:43], v[42:43], v[182:183] op_sel_hi:[1,0]
	v_pk_mul_f32 v[48:49], v[48:49], v[182:183] op_sel_hi:[1,0]
	v_pk_mul_f32 v[50:51], v[50:51], v[182:183] op_sel_hi:[1,0]
	v_pk_mul_f32 v[56:57], v[56:57], v[182:183] op_sel_hi:[1,0]
	v_pk_mul_f32 v[58:59], v[58:59], v[182:183] op_sel_hi:[1,0]

.Lat_noload_B0:
	v_add_u32_e32 v193, s44, v164
	v_add_u32_e32 v252, s1, v168
	s_setprio 0
	ds_read_b128 v[204:207], v193
	ds_read_b128 v[208:211], v193 offset:6656
	ds_read_b128 v[212:215], v193 offset:13312
	ds_read_b128 v[216:219], v193 offset:19968
	ds_read_b128 v[220:223], v193 offset:64
	ds_read_b128 v[224:227], v193 offset:6720
	ds_read_b128 v[228:231], v193 offset:13376
	ds_read_b128 v[232:235], v193 offset:20032
	s_waitcnt lgkmcnt(7)
	v_mfma_f32_16x16x32_bf16 v[132:135], v[204:207], v[64:67], 0
	v_mfma_f32_16x16x32_bf16 v[136:139], v[204:207], v[88:91], 0
	ds_read_b128 v[204:207], v193 offset:128
	s_waitcnt lgkmcnt(7)
	v_mfma_f32_16x16x32_bf16 v[140:143], v[208:211], v[64:67], 0
	v_mfma_f32_16x16x32_bf16 v[144:147], v[208:211], v[88:91], 0
	ds_read_b128 v[208:211], v193 offset:6784
	s_waitcnt lgkmcnt(7)
	v_mfma_f32_16x16x32_bf16 v[148:151], v[212:215], v[64:67], 0
	v_mfma_f32_16x16x32_bf16 v[152:155], v[212:215], v[88:91], 0
	ds_read_b128 v[212:215], v193 offset:13440
	s_waitcnt lgkmcnt(7)
	v_mfma_f32_16x16x32_bf16 v[156:159], v[216:219], v[64:67], 0
	v_mfma_f32_16x16x32_bf16 v[160:163], v[216:219], v[88:91], 0
	ds_read_b128 v[216:219], v193 offset:20096
	s_waitcnt lgkmcnt(7)
	v_mfma_f32_16x16x32_bf16 v[132:135], v[220:223], v[68:71], v[132:135]
	v_mfma_f32_16x16x32_bf16 v[136:139], v[220:223], v[92:95], v[136:139]
	ds_read_b128 v[220:223], v193 offset:192
	s_waitcnt lgkmcnt(7)
	v_mfma_f32_16x16x32_bf16 v[140:143], v[224:227], v[68:71], v[140:143]
	v_mfma_f32_16x16x32_bf16 v[144:147], v[224:227], v[92:95], v[144:147]
	ds_read_b128 v[224:227], v193 offset:6848
	s_waitcnt lgkmcnt(7)
	v_mfma_f32_16x16x32_bf16 v[148:151], v[228:231], v[68:71], v[148:151]
	v_mfma_f32_16x16x32_bf16 v[152:155], v[228:231], v[92:95], v[152:155]
	ds_read_b128 v[228:231], v193 offset:13504
	s_waitcnt lgkmcnt(7)
	v_mfma_f32_16x16x32_bf16 v[156:159], v[232:235], v[68:71], v[156:159]
	v_mfma_f32_16x16x32_bf16 v[160:163], v[232:235], v[92:95], v[160:163]
	ds_read_b128 v[232:235], v193 offset:20160
	s_waitcnt lgkmcnt(7)
	v_mfma_f32_16x16x32_bf16 v[132:135], v[204:207], v[72:75], v[132:135]
	v_mfma_f32_16x16x32_bf16 v[136:139], v[204:207], v[96:99], v[136:139]
	ds_read_b128 v[204:207], v193 offset:256
	s_waitcnt lgkmcnt(7)
	v_mfma_f32_16x16x32_bf16 v[140:143], v[208:211], v[72:75], v[140:143]
	v_mfma_f32_16x16x32_bf16 v[144:147], v[208:211], v[96:99], v[144:147]
	ds_read_b128 v[208:211], v193 offset:6912
	s_waitcnt lgkmcnt(7)
	v_mfma_f32_16x16x32_bf16 v[148:151], v[212:215], v[72:75], v[148:151]
	v_mfma_f32_16x16x32_bf16 v[152:155], v[212:215], v[96:99], v[152:155]
	ds_read_b128 v[212:215], v193 offset:13568
	s_waitcnt lgkmcnt(7)
	v_mfma_f32_16x16x32_bf16 v[156:159], v[216:219], v[72:75], v[156:159]
	v_mfma_f32_16x16x32_bf16 v[160:163], v[216:219], v[96:99], v[160:163]
	ds_read_b128 v[216:219], v193 offset:20224
	s_waitcnt lgkmcnt(7)
	v_mfma_f32_16x16x32_bf16 v[132:135], v[220:223], v[76:79], v[132:135]
	v_mfma_f32_16x16x32_bf16 v[136:139], v[220:223], v[100:103], v[136:139]
	ds_read_b128 v[220:223], v193 offset:320
	s_waitcnt lgkmcnt(7)
	v_mfma_f32_16x16x32_bf16 v[140:143], v[224:227], v[76:79], v[140:143]
	v_mfma_f32_16x16x32_bf16 v[144:147], v[224:227], v[100:103], v[144:147]
	ds_read_b128 v[224:227], v193 offset:6976
	s_waitcnt lgkmcnt(7)
	v_mfma_f32_16x16x32_bf16 v[148:151], v[228:231], v[76:79], v[148:151]
	v_mfma_f32_16x16x32_bf16 v[152:155], v[228:231], v[100:103], v[152:155]
	ds_read_b128 v[228:231], v193 offset:13632
	s_waitcnt lgkmcnt(7)
	v_mfma_f32_16x16x32_bf16 v[156:159], v[232:235], v[76:79], v[156:159]
	v_mfma_f32_16x16x32_bf16 v[160:163], v[232:235], v[100:103], v[160:163]
	ds_read_b128 v[232:235], v193 offset:20288
	s_waitcnt lgkmcnt(7)
	v_mfma_f32_16x16x32_bf16 v[132:135], v[204:207], v[80:83], v[132:135]
	v_mfma_f32_16x16x32_bf16 v[136:139], v[204:207], v[104:107], v[136:139]
	ds_read_b128 v[204:207], v252
	s_waitcnt lgkmcnt(7)
	v_mfma_f32_16x16x32_bf16 v[140:143], v[208:211], v[80:83], v[140:143]
	v_mfma_f32_16x16x32_bf16 v[144:147], v[208:211], v[104:107], v[144:147]
	ds_read_b128 v[208:211], v252 offset:64
	s_waitcnt lgkmcnt(7)
	v_mfma_f32_16x16x32_bf16 v[148:151], v[212:215], v[80:83], v[148:151]
	v_mfma_f32_16x16x32_bf16 v[152:155], v[212:215], v[104:107], v[152:155]
	ds_read_b128 v[212:215], v252 offset:2560
	s_waitcnt lgkmcnt(7)
	v_mfma_f32_16x16x32_bf16 v[156:159], v[216:219], v[80:83], v[156:159]
	v_mfma_f32_16x16x32_bf16 v[160:163], v[216:219], v[104:107], v[160:163]
	ds_read_b128 v[216:219], v252 offset:2624
	s_waitcnt lgkmcnt(7)
	v_mfma_f32_16x16x32_bf16 v[132:135], v[220:223], v[84:87], v[132:135]
	v_mfma_f32_16x16x32_bf16 v[136:139], v[220:223], v[108:111], v[136:139]
	ds_read_b128 v[220:223], v252 offset:5120
	s_waitcnt lgkmcnt(7)
	v_mfma_f32_16x16x32_bf16 v[140:143], v[224:227], v[84:87], v[140:143]
	v_mfma_f32_16x16x32_bf16 v[144:147], v[224:227], v[108:111], v[144:147]
	ds_read_b128 v[224:227], v252 offset:5184
	s_waitcnt lgkmcnt(7)
	v_mfma_f32_16x16x32_bf16 v[148:151], v[228:231], v[84:87], v[148:151]
	v_mfma_f32_16x16x32_bf16 v[152:155], v[228:231], v[108:111], v[152:155]
	ds_read_b128 v[228:231], v252 offset:7680
	s_waitcnt lgkmcnt(7)
	v_mfma_f32_16x16x32_bf16 v[156:159], v[232:235], v[84:87], v[156:159]
	v_mfma_f32_16x16x32_bf16 v[160:163], v[232:235], v[108:111], v[160:163]
	ds_read_b128 v[232:235], v252 offset:7744
	s_setprio 1
	s_nop 6
	v_max3_f32 v199, v132, v133, v134
	v_max3_f32 v200, v136, v137, v138
	v_max3_f32 v199, v199, v135, v140
	v_max3_f32 v200, v200, v139, v144
	v_max3_f32 v199, v199, v141, v142
	v_max3_f32 v200, v200, v145, v146
	v_max3_f32 v199, v199, v143, v148
	v_max3_f32 v200, v200, v147, v152
	v_max3_f32 v199, v199, v149, v150
	v_max3_f32 v200, v200, v153, v154
	v_max3_f32 v199, v199, v151, v156
	v_max3_f32 v200, v200, v155, v160
	v_max3_f32 v199, v199, v157, v158
	v_max3_f32 v200, v200, v161, v162
	v_max_f32_e32 v199, v199, v159
	v_max_f32_e32 v200, v200, v163
	v_mov_b32_e32 v253, v199
	v_mov_b32_e32 v201, v200
	s_nop 1
	v_permlane16_swap_b32_e32 v199, v253
	v_permlane16_swap_b32_e32 v200, v201
	s_nop 0
	v_max_f32_e32 v199, v199, v253
	v_max_f32_e32 v200, v200, v201
	v_mov_b32_e32 v253, v199
	v_mov_b32_e32 v201, v200
	s_nop 1
	v_permlane32_swap_b32_e32 v199, v253
	v_permlane32_swap_b32_e32 v200, v201
	s_nop 0
	v_max_f32_e32 v199, v199, v253
	v_max_f32_e32 v200, v200, v201
	v_max_f32_e32 v199, v177, v199
	v_max_f32_e32 v200, v178, v200
	v_sub_f32_e32 v182, v177, v199
	v_sub_f32_e32 v202, v178, v200
	v_cmp_le_f32_e32 vcc, 0xc1000000, v182
	s_nop 1
	v_cndmask_b32_e32 v199, v199, v177, vcc
	v_cmp_le_f32_e32 vcc, 0xc1000000, v202
	s_nop 1
	v_cndmask_b32_e32 v200, v200, v178, vcc
	v_sub_f32_e32 v182, v177, v199
	v_sub_f32_e32 v202, v178, v200
	v_exp_f32_e32 v182, v182
	v_exp_f32_e32 v202, v202
	v_mov_b32_e32 v177, v199
	v_mov_b32_e32 v178, v200
	v_sub_f32_e32 v132, v132, v177
	v_sub_f32_e32 v136, v136, v178
	v_sub_f32_e32 v133, v133, v177
	v_sub_f32_e32 v137, v137, v178
	v_sub_f32_e32 v134, v134, v177
	v_sub_f32_e32 v138, v138, v178
	v_sub_f32_e32 v135, v135, v177
	v_sub_f32_e32 v139, v139, v178
	v_sub_f32_e32 v140, v140, v177
	v_sub_f32_e32 v144, v144, v178
	v_sub_f32_e32 v141, v141, v177
	v_sub_f32_e32 v145, v145, v178
	v_sub_f32_e32 v142, v142, v177
	v_sub_f32_e32 v146, v146, v178
	v_sub_f32_e32 v143, v143, v177
	v_sub_f32_e32 v147, v147, v178
	v_sub_f32_e32 v148, v148, v177
	v_sub_f32_e32 v152, v152, v178
	v_sub_f32_e32 v149, v149, v177
	v_sub_f32_e32 v153, v153, v178
	v_sub_f32_e32 v150, v150, v177
	v_sub_f32_e32 v154, v154, v178
	v_sub_f32_e32 v151, v151, v177
	v_sub_f32_e32 v155, v155, v178
	v_sub_f32_e32 v156, v156, v177
	v_sub_f32_e32 v160, v160, v178
	v_sub_f32_e32 v157, v157, v177
	v_sub_f32_e32 v161, v161, v178
	v_sub_f32_e32 v158, v158, v177
	v_sub_f32_e32 v162, v162, v178
	v_sub_f32_e32 v159, v159, v177
	v_sub_f32_e32 v163, v163, v178
	v_exp_f32_e32 v132, v132
	v_exp_f32_e32 v136, v136
	v_exp_f32_e32 v133, v133
	v_exp_f32_e32 v137, v137
	v_exp_f32_e32 v134, v134
	v_exp_f32_e32 v138, v138
	v_exp_f32_e32 v135, v135
	v_exp_f32_e32 v139, v139
	v_exp_f32_e32 v140, v140
	v_exp_f32_e32 v144, v144
	v_exp_f32_e32 v141, v141
	v_exp_f32_e32 v145, v145
	v_exp_f32_e32 v142, v142
	v_exp_f32_e32 v146, v146
	v_exp_f32_e32 v143, v143
	v_exp_f32_e32 v147, v147
	v_exp_f32_e32 v148, v148
	v_exp_f32_e32 v152, v152
	v_exp_f32_e32 v149, v149
	v_exp_f32_e32 v153, v153
	v_exp_f32_e32 v150, v150
	v_exp_f32_e32 v154, v154
	v_exp_f32_e32 v151, v151
	v_exp_f32_e32 v155, v155
	v_exp_f32_e32 v156, v156
	v_exp_f32_e32 v160, v160
	v_exp_f32_e32 v157, v157
	v_exp_f32_e32 v161, v161
	v_exp_f32_e32 v158, v158
	v_exp_f32_e32 v162, v162
	v_exp_f32_e32 v159, v159
	v_exp_f32_e32 v163, v163
	v_cmp_eq_f32_e32 vcc, 1.0, v182
	s_cmp_eq_u64 vcc, exec
	s_cbranch_scc1 .Lat_noscale0_B0
	v_pk_mul_f32 v[0:1], v[0:1], v[182:183] op_sel_hi:[1,0]
	v_pk_mul_f32 v[2:3], v[2:3], v[182:183] op_sel_hi:[1,0]
	v_pk_mul_f32 v[8:9], v[8:9], v[182:183] op_sel_hi:[1,0]
	v_pk_mul_f32 v[10:11], v[10:11], v[182:183] op_sel_hi:[1,0]
	v_pk_mul_f32 v[16:17], v[16:17], v[182:183] op_sel_hi:[1,0]
	v_pk_mul_f32 v[18:19], v[18:19], v[182:183] op_sel_hi:[1,0]
	v_pk_mul_f32 v[24:25], v[24:25], v[182:183] op_sel_hi:[1,0]
	v_pk_mul_f32 v[26:27], v[26:27], v[182:183] op_sel_hi:[1,0]
	v_pk_mul_f32 v[32:33], v[32:33], v[182:183] op_sel_hi:[1,0]
	v_pk_mul_f32 v[34:35], v[34:35], v[182:183] op_sel_hi:[1,0]
	v_pk_mul_f32 v[40:41], v[40:41], v[182:183] op_sel_hi:[1,0]
	v_pk_mul_f32 v[42:43], v[42:43], v[182:183] op_sel_hi:[1,0]
	v_pk_mul_f32 v[48:49], v[48:49], v[182:183] op_sel_hi:[1,0]
	v_pk_mul_f32 v[50:51], v[50:51], v[182:183] op_sel_hi:[1,0]
	v_pk_mul_f32 v[56:57], v[56:57], v[182:183] op_sel_hi:[1,0]
	v_pk_mul_f32 v[58:59], v[58:59], v[182:183] op_sel_hi:[1,0]

.Lat_noload_B:
	v_add_u32_e32 v193, s44, v164
	v_add_u32_e32 v194, s0, v168
	v_add_u32_e32 v252, s1, v168
	s_setprio 0
	s_nop 0
	v_mfma_f32_16x16x32_bf16 v[0:3], v[204:207], v[236:239], v[0:3]
	v_mfma_f32_16x16x32_bf16 v[4:7], v[204:207], v[244:247], v[4:7]
	ds_read_b128 v[204:207], v194 offset:10240
	v_mfma_f32_16x16x32_bf16 v[0:3], v[208:211], v[240:243], v[0:3]
	v_mfma_f32_16x16x32_bf16 v[4:7], v[208:211], v[248:251], v[4:7]
	ds_read_b128 v[208:211], v194 offset:10304
	v_mfma_f32_16x16x32_bf16 v[8:11], v[212:215], v[236:239], v[8:11]
	v_mfma_f32_16x16x32_bf16 v[12:15], v[212:215], v[244:247], v[12:15]
	ds_read_b128 v[212:215], v194 offset:12800
	v_mfma_f32_16x16x32_bf16 v[8:11], v[216:219], v[240:243], v[8:11]
	v_mfma_f32_16x16x32_bf16 v[12:15], v[216:219], v[248:251], v[12:15]
	ds_read_b128 v[216:219], v194 offset:12864
	v_mfma_f32_16x16x32_bf16 v[16:19], v[220:223], v[236:239], v[16:19]
	v_mfma_f32_16x16x32_bf16 v[20:23], v[220:223], v[244:247], v[20:23]
	ds_read_b128 v[220:223], v194 offset:15360
	v_mfma_f32_16x16x32_bf16 v[16:19], v[224:227], v[240:243], v[16:19]
	v_mfma_f32_16x16x32_bf16 v[20:23], v[224:227], v[248:251], v[20:23]
	ds_read_b128 v[224:227], v194 offset:15424
	v_mfma_f32_16x16x32_bf16 v[24:27], v[228:231], v[236:239], v[24:27]
	v_mfma_f32_16x16x32_bf16 v[28:31], v[228:231], v[244:247], v[28:31]
	ds_read_b128 v[228:231], v194 offset:17920
	v_mfma_f32_16x16x32_bf16 v[24:27], v[232:235], v[240:243], v[24:27]
	v_mfma_f32_16x16x32_bf16 v[28:31], v[232:235], v[248:251], v[28:31]
	ds_read_b128 v[232:235], v194 offset:17984
	s_waitcnt lgkmcnt(7)
	v_mfma_f32_16x16x32_bf16 v[32:35], v[204:207], v[236:239], v[32:35]
	v_mfma_f32_16x16x32_bf16 v[36:39], v[204:207], v[244:247], v[36:39]
	ds_read_b128 v[204:207], v193
	s_waitcnt lgkmcnt(7)
	v_mfma_f32_16x16x32_bf16 v[32:35], v[208:211], v[240:243], v[32:35]
	v_mfma_f32_16x16x32_bf16 v[36:39], v[208:211], v[248:251], v[36:39]
	ds_read_b128 v[208:211], v193 offset:6656
	s_waitcnt lgkmcnt(7)
	v_mfma_f32_16x16x32_bf16 v[40:43], v[212:215], v[236:239], v[40:43]
	v_mfma_f32_16x16x32_bf16 v[44:47], v[212:215], v[244:247], v[44:47]
	ds_read_b128 v[212:215], v193 offset:13312
	s_waitcnt lgkmcnt(7)
	v_mfma_f32_16x16x32_bf16 v[40:43], v[216:219], v[240:243], v[40:43]
	v_mfma_f32_16x16x32_bf16 v[44:47], v[216:219], v[248:251], v[44:47]
	ds_read_b128 v[216:219], v193 offset:19968
	s_waitcnt lgkmcnt(7)
	v_mfma_f32_16x16x32_bf16 v[48:51], v[220:223], v[236:239], v[48:51]
	v_mfma_f32_16x16x32_bf16 v[52:55], v[220:223], v[244:247], v[52:55]
	ds_read_b128 v[220:223], v193 offset:64
	s_waitcnt lgkmcnt(7)
	v_mfma_f32_16x16x32_bf16 v[48:51], v[224:227], v[240:243], v[48:51]
	v_mfma_f32_16x16x32_bf16 v[52:55], v[224:227], v[248:251], v[52:55]
	ds_read_b128 v[224:227], v193 offset:6720
	s_waitcnt lgkmcnt(7)
	v_mfma_f32_16x16x32_bf16 v[56:59], v[228:231], v[236:239], v[56:59]
	v_mfma_f32_16x16x32_bf16 v[60:63], v[228:231], v[244:247], v[60:63]
	ds_read_b128 v[228:231], v193 offset:13376
	s_waitcnt lgkmcnt(7)
	v_mfma_f32_16x16x32_bf16 v[56:59], v[232:235], v[240:243], v[56:59]
	v_mfma_f32_16x16x32_bf16 v[60:63], v[232:235], v[248:251], v[60:63]
	ds_read_b128 v[232:235], v193 offset:20032
	s_setprio 1
	s_setprio 0
	s_waitcnt lgkmcnt(7)
	v_mfma_f32_16x16x32_bf16 v[132:135], v[204:207], v[64:67], 0
	v_mfma_f32_16x16x32_bf16 v[136:139], v[204:207], v[88:91], 0
	ds_read_b128 v[204:207], v193 offset:128
	s_waitcnt lgkmcnt(7)
	v_mfma_f32_16x16x32_bf16 v[140:143], v[208:211], v[64:67], 0
	v_mfma_f32_16x16x32_bf16 v[144:147], v[208:211], v[88:91], 0
	ds_read_b128 v[208:211], v193 offset:6784
	s_waitcnt lgkmcnt(7)
	v_mfma_f32_16x16x32_bf16 v[148:151], v[212:215], v[64:67], 0
	v_mfma_f32_16x16x32_bf16 v[152:155], v[212:215], v[88:91], 0
	ds_read_b128 v[212:215], v193 offset:13440
	s_waitcnt lgkmcnt(7)
	v_mfma_f32_16x16x32_bf16 v[156:159], v[216:219], v[64:67], 0
	v_mfma_f32_16x16x32_bf16 v[160:163], v[216:219], v[88:91], 0
	ds_read_b128 v[216:219], v193 offset:20096
	s_waitcnt lgkmcnt(7)
	v_mfma_f32_16x16x32_bf16 v[132:135], v[220:223], v[68:71], v[132:135]
	v_mfma_f32_16x16x32_bf16 v[136:139], v[220:223], v[92:95], v[136:139]
	ds_read_b128 v[220:223], v193 offset:192
	s_waitcnt lgkmcnt(7)
	v_mfma_f32_16x16x32_bf16 v[140:143], v[224:227], v[68:71], v[140:143]
	v_mfma_f32_16x16x32_bf16 v[144:147], v[224:227], v[92:95], v[144:147]
	ds_read_b128 v[224:227], v193 offset:6848
	s_waitcnt lgkmcnt(7)
	v_mfma_f32_16x16x32_bf16 v[148:151], v[228:231], v[68:71], v[148:151]
	v_mfma_f32_16x16x32_bf16 v[152:155], v[228:231], v[92:95], v[152:155]
	ds_read_b128 v[228:231], v193 offset:13504
	s_waitcnt lgkmcnt(7)
	v_mfma_f32_16x16x32_bf16 v[156:159], v[232:235], v[68:71], v[156:159]
	v_mfma_f32_16x16x32_bf16 v[160:163], v[232:235], v[92:95], v[160:163]
	ds_read_b128 v[232:235], v193 offset:20160
	s_waitcnt lgkmcnt(7)
	v_mfma_f32_16x16x32_bf16 v[132:135], v[204:207], v[72:75], v[132:135]
	v_mfma_f32_16x16x32_bf16 v[136:139], v[204:207], v[96:99], v[136:139]
	ds_read_b128 v[204:207], v193 offset:256
	s_waitcnt lgkmcnt(7)
	v_mfma_f32_16x16x32_bf16 v[140:143], v[208:211], v[72:75], v[140:143]
	v_mfma_f32_16x16x32_bf16 v[144:147], v[208:211], v[96:99], v[144:147]
	ds_read_b128 v[208:211], v193 offset:6912
	s_waitcnt lgkmcnt(7)
	v_mfma_f32_16x16x32_bf16 v[148:151], v[212:215], v[72:75], v[148:151]
	v_mfma_f32_16x16x32_bf16 v[152:155], v[212:215], v[96:99], v[152:155]
	ds_read_b128 v[212:215], v193 offset:13568
	s_waitcnt lgkmcnt(7)
	v_mfma_f32_16x16x32_bf16 v[156:159], v[216:219], v[72:75], v[156:159]
	v_mfma_f32_16x16x32_bf16 v[160:163], v[216:219], v[96:99], v[160:163]
	ds_read_b128 v[216:219], v193 offset:20224
	s_waitcnt lgkmcnt(7)
	v_mfma_f32_16x16x32_bf16 v[132:135], v[220:223], v[76:79], v[132:135]
	v_mfma_f32_16x16x32_bf16 v[136:139], v[220:223], v[100:103], v[136:139]
	ds_read_b128 v[220:223], v193 offset:320
	s_waitcnt lgkmcnt(7)
	v_mfma_f32_16x16x32_bf16 v[140:143], v[224:227], v[76:79], v[140:143]
	v_mfma_f32_16x16x32_bf16 v[144:147], v[224:227], v[100:103], v[144:147]
	ds_read_b128 v[224:227], v193 offset:6976
	s_waitcnt lgkmcnt(7)
	v_mfma_f32_16x16x32_bf16 v[148:151], v[228:231], v[76:79], v[148:151]
	v_mfma_f32_16x16x32_bf16 v[152:155], v[228:231], v[100:103], v[152:155]
	ds_read_b128 v[228:231], v193 offset:13632
	s_waitcnt lgkmcnt(7)
	v_mfma_f32_16x16x32_bf16 v[156:159], v[232:235], v[76:79], v[156:159]
	v_mfma_f32_16x16x32_bf16 v[160:163], v[232:235], v[100:103], v[160:163]
	ds_read_b128 v[232:235], v193 offset:20288
	s_waitcnt lgkmcnt(7)
	v_mfma_f32_16x16x32_bf16 v[132:135], v[204:207], v[80:83], v[132:135]
	v_mfma_f32_16x16x32_bf16 v[136:139], v[204:207], v[104:107], v[136:139]
	ds_read_b128 v[204:207], v252
	s_waitcnt lgkmcnt(7)
	v_mfma_f32_16x16x32_bf16 v[140:143], v[208:211], v[80:83], v[140:143]
	v_mfma_f32_16x16x32_bf16 v[144:147], v[208:211], v[104:107], v[144:147]
	ds_read_b128 v[208:211], v252 offset:64
	s_waitcnt lgkmcnt(7)
	v_mfma_f32_16x16x32_bf16 v[148:151], v[212:215], v[80:83], v[148:151]
	v_mfma_f32_16x16x32_bf16 v[152:155], v[212:215], v[104:107], v[152:155]
	ds_read_b128 v[212:215], v252 offset:2560
	s_waitcnt lgkmcnt(7)
	v_mfma_f32_16x16x32_bf16 v[156:159], v[216:219], v[80:83], v[156:159]
	v_mfma_f32_16x16x32_bf16 v[160:163], v[216:219], v[104:107], v[160:163]
	ds_read_b128 v[216:219], v252 offset:2624
	s_waitcnt lgkmcnt(7)
	v_mfma_f32_16x16x32_bf16 v[132:135], v[220:223], v[84:87], v[132:135]
	v_mfma_f32_16x16x32_bf16 v[136:139], v[220:223], v[108:111], v[136:139]
	ds_read_b128 v[220:223], v252 offset:5120
	s_waitcnt lgkmcnt(7)
	v_mfma_f32_16x16x32_bf16 v[140:143], v[224:227], v[84:87], v[140:143]
	v_mfma_f32_16x16x32_bf16 v[144:147], v[224:227], v[108:111], v[144:147]
	ds_read_b128 v[224:227], v252 offset:5184
	s_waitcnt lgkmcnt(7)
	v_mfma_f32_16x16x32_bf16 v[148:151], v[228:231], v[84:87], v[148:151]
	v_mfma_f32_16x16x32_bf16 v[152:155], v[228:231], v[108:111], v[152:155]
	ds_read_b128 v[228:231], v252 offset:7680
	s_waitcnt lgkmcnt(7)
	v_mfma_f32_16x16x32_bf16 v[156:159], v[232:235], v[84:87], v[156:159]
	v_mfma_f32_16x16x32_bf16 v[160:163], v[232:235], v[108:111], v[160:163]
	ds_read_b128 v[232:235], v252 offset:7744
	s_setprio 1
	s_nop 6
	v_max3_f32 v199, v132, v133, v134
	v_max3_f32 v200, v136, v137, v138
	v_max3_f32 v199, v199, v135, v140
	v_max3_f32 v200, v200, v139, v144
	v_max3_f32 v199, v199, v141, v142
	v_max3_f32 v200, v200, v145, v146
	v_max3_f32 v199, v199, v143, v148
	v_max3_f32 v200, v200, v147, v152
	v_max3_f32 v199, v199, v149, v150
	v_max3_f32 v200, v200, v153, v154
	v_max3_f32 v199, v199, v151, v156
	v_max3_f32 v200, v200, v155, v160
	v_max3_f32 v199, v199, v157, v158
	v_max3_f32 v200, v200, v161, v162
	v_max_f32_e32 v199, v199, v159
	v_max_f32_e32 v200, v200, v163
	v_mov_b32_e32 v253, v199
	v_mov_b32_e32 v201, v200
	s_nop 1
	v_permlane16_swap_b32_e32 v199, v253
	v_permlane16_swap_b32_e32 v200, v201
	s_nop 0
	v_max_f32_e32 v199, v199, v253
	v_max_f32_e32 v200, v200, v201
	v_mov_b32_e32 v253, v199
	v_mov_b32_e32 v201, v200
	s_nop 1
	v_permlane32_swap_b32_e32 v199, v253
	v_permlane32_swap_b32_e32 v200, v201
	s_nop 0
	v_max_f32_e32 v199, v199, v253
	v_max_f32_e32 v200, v200, v201
	v_max_f32_e32 v199, v177, v199
	v_max_f32_e32 v200, v178, v200
	v_sub_f32_e32 v182, v177, v199
	v_sub_f32_e32 v202, v178, v200
	v_cmp_le_f32_e32 vcc, 0xc1000000, v182
	s_nop 1
	v_cndmask_b32_e32 v199, v199, v177, vcc
	v_cmp_le_f32_e32 vcc, 0xc1000000, v202
	s_nop 1
	v_cndmask_b32_e32 v200, v200, v178, vcc
	v_sub_f32_e32 v182, v177, v199
	v_sub_f32_e32 v202, v178, v200
	v_exp_f32_e32 v182, v182
	v_exp_f32_e32 v202, v202
	v_mov_b32_e32 v177, v199
	v_mov_b32_e32 v178, v200
	v_sub_f32_e32 v132, v132, v177
	v_sub_f32_e32 v136, v136, v178
	v_sub_f32_e32 v133, v133, v177
	v_sub_f32_e32 v137, v137, v178
	v_sub_f32_e32 v134, v134, v177
	v_sub_f32_e32 v138, v138, v178
	v_sub_f32_e32 v135, v135, v177
	v_sub_f32_e32 v139, v139, v178
	v_sub_f32_e32 v140, v140, v177
	v_sub_f32_e32 v144, v144, v178
	v_sub_f32_e32 v141, v141, v177
	v_sub_f32_e32 v145, v145, v178
	v_sub_f32_e32 v142, v142, v177
	v_sub_f32_e32 v146, v146, v178
	v_sub_f32_e32 v143, v143, v177
	v_sub_f32_e32 v147, v147, v178
	v_sub_f32_e32 v148, v148, v177
	v_sub_f32_e32 v152, v152, v178
	v_sub_f32_e32 v149, v149, v177
	v_sub_f32_e32 v153, v153, v178
	v_sub_f32_e32 v150, v150, v177
	v_sub_f32_e32 v154, v154, v178
	v_sub_f32_e32 v151, v151, v177
	v_sub_f32_e32 v155, v155, v178
	v_sub_f32_e32 v156, v156, v177
	v_sub_f32_e32 v160, v160, v178
	v_sub_f32_e32 v157, v157, v177
	v_sub_f32_e32 v161, v161, v178
	v_sub_f32_e32 v158, v158, v177
	v_sub_f32_e32 v162, v162, v178
	v_sub_f32_e32 v159, v159, v177
	v_sub_f32_e32 v163, v163, v178
	v_exp_f32_e32 v132, v132
	v_exp_f32_e32 v136, v136
	v_exp_f32_e32 v133, v133
	v_exp_f32_e32 v137, v137
	v_exp_f32_e32 v134, v134
	v_exp_f32_e32 v138, v138
	v_exp_f32_e32 v135, v135
	v_exp_f32_e32 v139, v139
	v_exp_f32_e32 v140, v140
	v_exp_f32_e32 v144, v144
	v_exp_f32_e32 v141, v141
	v_exp_f32_e32 v145, v145
	v_exp_f32_e32 v142, v142
	v_exp_f32_e32 v146, v146
	v_exp_f32_e32 v143, v143
	v_exp_f32_e32 v147, v147
	v_exp_f32_e32 v148, v148
	v_exp_f32_e32 v152, v152
	v_exp_f32_e32 v149, v149
	v_exp_f32_e32 v153, v153
	v_exp_f32_e32 v150, v150
	v_exp_f32_e32 v154, v154
	v_exp_f32_e32 v151, v151
	v_exp_f32_e32 v155, v155
	v_exp_f32_e32 v156, v156
	v_exp_f32_e32 v160, v160
	v_exp_f32_e32 v157, v157
	v_exp_f32_e32 v161, v161
	v_exp_f32_e32 v158, v158
	v_exp_f32_e32 v162, v162
	v_exp_f32_e32 v159, v159
	v_exp_f32_e32 v163, v163
	v_cmp_eq_f32_e32 vcc, 1.0, v182
	s_cmp_eq_u64 vcc, exec
	s_cbranch_scc1 .Lat_noscale0_B
	v_pk_mul_f32 v[0:1], v[0:1], v[182:183] op_sel_hi:[1,0]
	v_pk_mul_f32 v[2:3], v[2:3], v[182:183] op_sel_hi:[1,0]
	v_pk_mul_f32 v[8:9], v[8:9], v[182:183] op_sel_hi:[1,0]
	v_pk_mul_f32 v[10:11], v[10:11], v[182:183] op_sel_hi:[1,0]
	v_pk_mul_f32 v[16:17], v[16:17], v[182:183] op_sel_hi:[1,0]
	v_pk_mul_f32 v[18:19], v[18:19], v[182:183] op_sel_hi:[1,0]
	v_pk_mul_f32 v[24:25], v[24:25], v[182:183] op_sel_hi:[1,0]
	v_pk_mul_f32 v[26:27], v[26:27], v[182:183] op_sel_hi:[1,0]
	v_pk_mul_f32 v[32:33], v[32:33], v[182:183] op_sel_hi:[1,0]
	v_pk_mul_f32 v[34:35], v[34:35], v[182:183] op_sel_hi:[1,0]
	v_pk_mul_f32 v[40:41], v[40:41], v[182:183] op_sel_hi:[1,0]
	v_pk_mul_f32 v[42:43], v[42:43], v[182:183] op_sel_hi:[1,0]
	v_pk_mul_f32 v[48:49], v[48:49], v[182:183] op_sel_hi:[1,0]
	v_pk_mul_f32 v[50:51], v[50:51], v[182:183] op_sel_hi:[1,0]
	v_pk_mul_f32 v[56:57], v[56:57], v[182:183] op_sel_hi:[1,0]
	v_pk_mul_f32 v[58:59], v[58:59], v[182:183] op_sel_hi:[1,0]
